# sel output: exclusive prefix of per-lane selected counts via DPP scan (row_shr 1/2/4/8 + row_bcast 15/31) instead of six ds_bpermute round trips
# speedup vs baseline: 1.0017x; 1.0017x over previous
.LBB0_1099:
	v_bcnt_u32_b32 v9, v0, 0
	v_bcnt_u32_b32 v10, v3, 0
	v_bcnt_u32_b32 v8, v2, 0
	v_bcnt_u32_b32 v9, v1, v9
	v_add3_u32 v9, v9, v8, v10
	v_mov_b32_e32 v17, v9
	s_nop 1
	v_add_u32_dpp v17, v17, v17 row_shr:1 row_mask:0xf bank_mask:0xf bound_ctrl:1
	s_nop 1
	v_add_u32_dpp v17, v17, v17 row_shr:2 row_mask:0xf bank_mask:0xf bound_ctrl:1
	s_nop 1
	v_add_u32_dpp v17, v17, v17 row_shr:4 row_mask:0xf bank_mask:0xf bound_ctrl:1
	s_nop 1
	v_add_u32_dpp v17, v17, v17 row_shr:8 row_mask:0xf bank_mask:0xf bound_ctrl:1
	s_nop 1
	v_add_u32_dpp v17, v17, v17 row_bcast:15 row_mask:0xa bank_mask:0xf
	s_nop 1
	v_add_u32_dpp v17, v17, v17 row_bcast:31 row_mask:0xc bank_mask:0xf
	v_sub_u32_e32 v9, v17, v9
	v_cmp_ne_u32_e32 vcc, 0, v3
	s_and_saveexec_b64 s[6:7], vcc
	s_cbranch_execz .LBB0_1103
	v_mov_b32_e32 v11, v9
	v_add_u32_e32 v9, v9, v10
	v_add_u32_e32 v10, 1, v10
	v_lshl_add_u32 v11, v11, 2, s40
	s_mov_b64 s[8:9], 0
